# P3a: group members with odd index run their quarter of the dilated-pattern combine before their two retention units (bandwidth-bound and latency-bound work overlap chip-wide), on top of the P0 rotatio
# baseline (speedup 1.0000x reference)
.LBB0_567:
	s_xor_b64 s[42:43], s[0:1], -1
	s_lshr_b32 s0, s88, 2
	s_and_b32 s44, s0, 0x3ffffff8
	s_or_b32 s40, s44, s53
	s_lshl_b32 s36, s40, 6
	s_mov_b32 s37, 0
	s_bfe_u32 s52, s88, 0x20003
	s_lshl_b64 s[0:1], s[36:37], 2
	s_add_u32 s0, s96, s0
	s_addc_u32 s1, s97, s1
	s_add_u32 s38, s0, 0x84000
	s_addc_u32 s39, s1, 0
	s_cmp_lt_i32 s76, 4
	s_cselect_b64 s[0:1], -1, 0
	s_and_b64 s[24:25], s[0:1], s[2:3]
	s_andn2_b64 vcc, exec, s[24:25]
	v_lshlrev_b32_e32 v230, 3, v226
	v_lshrrev_b32_e32 v205, 3, v226
	v_and_b32_e32 v228, 31, v226
	v_lshrrev_b32_e32 v229, 5, v227
	v_lshlrev_b32_e32 v192, 4, v226
	s_cbranch_vccnz .LBB0_706
	s_mov_b32 s99, 0
	s_bitcmp1_b32 s52, 0
	s_cbranch_scc0 .Lretb_start
	s_mov_b32 s99, 1
	s_branch .Lcomb_start

.LBB0_588:
	v_add_u32_e32 v113, v161, v159
	v_sub_u32_e32 v115, v159, v89
	v_sub_u32_e32 v124, v159, v88
	v_sub_u32_e32 v138, v159, v91
	v_sub_u32_e32 v139, v159, v90
	v_sub_u32_e32 v140, v159, v93
	v_sub_u32_e32 v141, v159, v92
	v_sub_u32_e32 v142, v159, v95
	v_sub_u32_e32 v143, v159, v94
	v_cvt_f32_u32_e32 v39, v113
	v_cvt_f32_u32_e32 v40, v124
	v_cvt_f32_u32_e32 v41, v115
	v_cvt_f32_u32_e32 v42, v139
	v_cvt_f32_u32_e32 v43, v138
	v_cvt_f32_u32_e32 v44, v141
	v_cvt_f32_u32_e32 v45, v140
	v_cvt_f32_u32_e32 v46, v143
	v_cvt_f32_u32_e32 v47, v142
	ds_read_b128 v[32:35], v162
	ds_read_b128 v[84:87], v162 offset:32
	ds_read_b128 v[102:105], v162 offset:64
	ds_read_b128 v[106:109], v162 offset:96
	v_add_u32_e32 v36, 0xffffdc00, v160
	v_add_u32_e32 v37, 0xfffffc00, v160
	v_add_u32_e32 v38, 0xffffe000, v160
	ds_read_b64_tr_b16 v[120:121], v36
	ds_read_b64_tr_b16 v[122:123], v36 offset:512
	ds_read_b64_tr_b16 v[116:117], v37
	ds_read_b64_tr_b16 v[118:119], v37 offset:512
	s_waitcnt lgkmcnt(0)
	ds_read_b64_tr_b16 v[130:131], v38
	ds_read_b64_tr_b16 v[132:133], v38 offset:512
	ds_read_b64_tr_b16 v[126:127], v160
	ds_read_b64_tr_b16 v[128:129], v160 offset:512
	s_waitcnt lgkmcnt(0)
	v_mul_f32_e32 v154, v151, v39
	v_mul_f32_e32 v155, v151, v40
	v_mul_f32_e32 v163, v151, v41
	v_mul_f32_e32 v164, v151, v42
	v_mul_f32_e32 v165, v151, v43
	v_mul_f32_e32 v166, v151, v44
	v_mul_f32_e32 v167, v151, v45
	v_mul_f32_e32 v168, v151, v46
	v_mul_f32_e32 v169, v151, v47
	s_waitcnt lgkmcnt(3)
	v_mfma_f32_32x32x16_bf16 v[32:47], v[32:35], v[64:67], 0
	v_add_u32_e32 v152, -1, v113
	v_sub_u32_e32 v144, v159, v97
	v_sub_u32_e32 v145, v159, v96
	v_sub_u32_e32 v146, v159, v99
	v_sub_u32_e32 v147, v159, v98
	v_sub_u32_e32 v148, v159, v101
	v_sub_u32_e32 v149, v159, v100
	s_waitcnt lgkmcnt(2)
	v_mfma_f32_32x32x16_bf16 v[32:47], v[84:87], v[68:71], v[32:47]
	v_cvt_f32_u32_e32 v153, v152
	v_cvt_f32_u32_e32 v110, v145
	v_cvt_f32_u32_e32 v111, v144
	v_cvt_f32_u32_e32 v134, v147
	v_cvt_f32_u32_e32 v135, v146
	v_cvt_f32_u32_e32 v136, v149
	v_cvt_f32_u32_e32 v137, v148
	s_waitcnt lgkmcnt(1)
	v_mfma_f32_32x32x16_bf16 v[32:47], v[102:105], v[72:75], v[32:47]
	v_mul_f32_e32 v153, v151, v153
	v_mul_f32_e32 v170, v151, v110
	v_mul_f32_e32 v171, v151, v111
	v_mul_f32_e32 v173, v151, v134
	v_mul_f32_e32 v174, v151, v135
	v_mul_f32_e32 v136, v151, v136
	v_mul_f32_e32 v137, v151, v137
	s_waitcnt lgkmcnt(0)
	v_mfma_f32_32x32x16_bf16 v[32:47], v[106:109], v[76:79], v[32:47]
	v_exp_f32_e32 v154, v154
	v_exp_f32_e32 v110, v155
	v_exp_f32_e32 v111, v163
	v_exp_f32_e32 v84, v164
	v_exp_f32_e32 v85, v165
	v_exp_f32_e32 v86, v166
	v_exp_f32_e32 v87, v167
	v_exp_f32_e32 v153, v153
	v_exp_f32_e32 v134, v168
	v_exp_f32_e32 v135, v169
	v_exp_f32_e32 v102, v170
	v_exp_f32_e32 v103, v171
	v_exp_f32_e32 v104, v173
	v_exp_f32_e32 v105, v174
	v_exp_f32_e32 v136, v136
	v_exp_f32_e32 v137, v137
	v_mul_f32_e32 v106, v154, v32
	v_mul_f32_e32 v107, v153, v33
	v_cmp_lt_i32_e32 vcc, -1, v152
	v_pk_mul_f32 v[32:33], v[110:111], v[34:35]
	v_pk_mul_f32 v[34:35], v[84:85], v[36:37]
	v_pk_mul_f32 v[36:37], v[86:87], v[38:39]
	v_pk_mul_f32 v[38:39], v[134:135], v[40:41]
	v_pk_mul_f32 v[40:41], v[102:103], v[42:43]
	v_pk_mul_f32 v[42:43], v[104:105], v[44:45]
	v_pk_mul_f32 v[44:45], v[136:137], v[46:47]
	v_cmp_lt_i32_e64 s[0:1], -1, v113
	v_cndmask_b32_e32 v47, 0, v107, vcc
	v_cvt_pk_bf16_f32 v33, v32, v33
	v_cmp_lt_i32_e32 vcc, -1, v124
	v_cvt_pk_bf16_f32 v34, v34, v35
	v_cvt_pk_bf16_f32 v35, v36, v37
	v_cndmask_b32_e64 v46, 0, v106, s[0:1]
	v_cmp_lt_i32_e64 s[0:1], -1, v139
	v_cmp_lt_i32_e64 s[4:5], -1, v141
	v_cvt_pk_bf16_f32 v36, v38, v39
	v_cvt_pk_bf16_f32 v37, v40, v41
	v_cvt_pk_bf16_f32 v39, v44, v45
	v_lshrrev_b32_e32 v40, 16, v34
	v_cmp_lt_i32_e64 s[14:15], -1, v138
	v_lshrrev_b32_e32 v41, 16, v35
	v_cmp_lt_i32_e64 s[16:17], -1, v140
	v_cndmask_b32_e32 v45, 0, v33, vcc
	v_lshrrev_b32_e32 v33, 16, v33
	v_cmp_lt_i32_e32 vcc, -1, v115
	v_cndmask_b32_e64 v34, 0, v34, s[0:1]
	v_cndmask_b32_e64 v35, 0, v35, s[4:5]
	v_cndmask_b32_e32 v33, 0, v33, vcc
	v_cndmask_b32_e64 v40, 0, v40, s[14:15]
	v_cndmask_b32_e64 v41, 0, v41, s[16:17]
	v_cvt_pk_bf16_f32 v32, v46, v47
	v_perm_b32 v33, v33, v45, s3
	v_perm_b32 v34, v40, v34, s3
	v_perm_b32 v35, v41, v35, s3
	v_cmp_lt_i32_e64 s[6:7], -1, v143
	v_cvt_pk_bf16_f32 v38, v42, v43
	v_mfma_f32_32x32x16_bf16 v[0:15], v[120:123], v[32:35], v[0:15]
	v_cmp_lt_i32_e64 s[8:9], -1, v145
	v_cmp_lt_i32_e64 s[10:11], -1, v147
	v_cmp_lt_i32_e64 s[12:13], -1, v149
	v_lshrrev_b32_e32 v42, 16, v37
	v_cmp_lt_i32_e64 s[18:19], -1, v144
	v_lshrrev_b32_e32 v43, 16, v38
	v_cmp_lt_i32_e64 s[20:21], -1, v146
	v_mfma_f32_32x32x16_bf16 v[16:31], v[116:119], v[32:35], v[16:31]
	v_lshrrev_b32_e32 v44, 16, v39
	v_cmp_lt_i32_e64 s[22:23], -1, v148
	v_cndmask_b32_e64 v40, 0, v36, s[6:7]
	v_lshrrev_b32_e32 v36, 16, v36
	v_cmp_lt_i32_e32 vcc, -1, v142
	v_cndmask_b32_e64 v37, 0, v37, s[8:9]
	v_cndmask_b32_e64 v38, 0, v38, s[10:11]
	v_cndmask_b32_e64 v39, 0, v39, s[12:13]
	v_cndmask_b32_e32 v36, 0, v36, vcc
	v_cndmask_b32_e64 v33, 0, v42, s[18:19]
	v_cndmask_b32_e64 v34, 0, v43, s[20:21]
	v_cndmask_b32_e64 v35, 0, v44, s[22:23]
	v_perm_b32 v32, v36, v40, s3
	v_perm_b32 v33, v33, v37, s3
	v_perm_b32 v34, v34, v38, s3
	v_perm_b32 v35, v35, v39, s3
	s_add_i32 s2, s2, -1
	v_subrev_u32_e32 v159, 32, v159
	v_mfma_f32_32x32x16_bf16 v[0:15], v[130:133], v[32:35], v[0:15]
	v_add_u32_e32 v162, 0x1200, v162
	s_cmp_lg_u32 s2, 0
	v_add_u32_e32 v160, 0x800, v160
	v_mfma_f32_32x32x16_bf16 v[16:31], v[126:129], v[32:35], v[16:31]
	s_cbranch_scc1 .LBB0_588
	v_lshlrev_b64 v[32:33], 12, v[82:83]
	v_readlane_b32 s4, v254, 0
	v_lshlrev_b32_e32 v36, 11, v82
	v_and_b32_e32 v32, 0xfff00000, v32
	v_readlane_b32 s6, v254, 2
	v_readlane_b32 s7, v254, 3
	s_waitcnt vmcnt(0)
	v_lshlrev_b32_e32 v40, 16, v62
	v_and_b32_e32 v38, 0xffff0000, v62
	v_lshl_add_u64 v[34:35], s[6:7], 0, v[32:33]
	v_and_b32_e32 v32, 0x7f800, v36
	v_mul_f32_e32 v36, 0xbfb8aa3b, v40
	v_mul_f32_e32 v37, 0xbfb8aa3b, v38
	v_exp_f32_e32 v36, v36
	v_exp_f32_e32 v37, v37
	v_mov_b32_e32 v33, 0
	v_lshl_add_u64 v[34:35], v[34:35], 0, v[32:33]
	v_lshlrev_b32_e32 v45, 16, v61
	v_pk_add_f32 v[36:37], v[36:37], 1.0 op_sel_hi:[1,0]
	v_and_b32_e32 v46, 0xffff0000, v61
	v_lshlrev_b32_e32 v66, 16, v63
	v_and_b32_e32 v44, 0xffff0000, v63
	v_lshlrev_b32_e32 v71, 16, v58
	v_rcp_f32_e32 v32, v37
	s_nop 0
	v_mul_f32_e32 v37, v38, v32
	v_mul_f32_e32 v38, 0xbfb8aa3b, v45
	v_mul_f32_e32 v39, 0xbfb8aa3b, v46
	v_exp_f32_e32 v38, v38
	v_exp_f32_e32 v39, v39
	s_nop 0
	v_pk_add_f32 v[38:39], v[38:39], 1.0 op_sel_hi:[1,0]
	v_rcp_f32_e32 v32, v36
	s_nop 0
	v_mul_f32_e32 v36, v40, v32
	v_and_b32_e32 v58, 0xffff0000, v58
	v_rcp_f32_e32 v32, v39
	s_nop 0
	v_mul_f32_e32 v39, v46, v32
	v_lshlrev_b32_e32 v78, 16, v59
	v_lshlrev_b32_e32 v42, 16, v60
	v_and_b32_e32 v43, 0xffff0000, v60
	v_mul_f32_e32 v40, 0xbfb8aa3b, v42
	v_mul_f32_e32 v41, 0xbfb8aa3b, v43
	v_exp_f32_e32 v40, v40
	v_exp_f32_e32 v41, v41
	v_rcp_f32_e32 v32, v38
	s_nop 0
	v_mul_f32_e32 v38, v45, v32
	v_and_b32_e32 v76, 0xffff0000, v59
	v_lshlrev_b32_e32 v77, 16, v57
	v_pk_add_f32 v[40:41], v[40:41], 1.0 op_sel_hi:[1,0]
	v_and_b32_e32 v57, 0xffff0000, v57
	v_div_scale_f32 v67, s[0:1], v41, v41, v43
	v_rcp_f32_e32 v68, v67
	s_waitcnt lgkmcnt(0)
	s_barrier
	v_rcp_f32_e32 v45, v41
	s_nop 0
	v_mul_f32_e32 v41, v43, v45
	ds_write2_b32 v172, v0, v1 offset1:1
	ds_write2_b32 v172, v2, v3 offset0:2 offset1:3
	ds_write2_b32 v172, v4, v5 offset0:8 offset1:9
	ds_write2_b32 v172, v6, v7 offset0:10 offset1:11
	ds_write2_b32 v172, v8, v9 offset0:16 offset1:17
	ds_write2_b32 v172, v10, v11 offset0:18 offset1:19
	ds_write2_b32 v172, v12, v13 offset0:24 offset1:25
	ds_write2_b32 v172, v14, v15 offset0:26 offset1:27
	ds_write2_b32 v172, v16, v17 offset0:40 offset1:41
	ds_write2_b32 v172, v18, v19 offset0:42 offset1:43
	ds_write2_b32 v172, v20, v21 offset0:48 offset1:49
	ds_write2_b32 v172, v22, v23 offset0:50 offset1:51
	ds_write2_b32 v172, v24, v25 offset0:56 offset1:57
	ds_write2_b32 v172, v26, v27 offset0:58 offset1:59
	ds_write2_b32 v172, v28, v29 offset0:64 offset1:65
	ds_write2_b32 v172, v30, v31 offset0:66 offset1:67
	v_rcp_f32_e32 v43, v40
	s_nop 0
	v_mul_f32_e32 v40, v42, v43
	v_mul_f32_e32 v42, 0xbfb8aa3b, v66
	v_mul_f32_e32 v43, 0xbfb8aa3b, v44
	v_exp_f32_e32 v42, v42
	v_exp_f32_e32 v43, v43
	s_waitcnt lgkmcnt(0)
	s_barrier
	v_pk_add_f32 v[42:43], v[42:43], 1.0 op_sel_hi:[1,0]
	v_lshlrev_b32_e32 v79, 16, v56
	global_load_dwordx4 v[16:19], v[80:81], off offset:48
	global_load_dwordx4 v[20:23], v[80:81], off offset:32
	global_load_dwordx4 v[24:27], v[80:81], off offset:16
	global_load_dwordx4 v[28:31], v[80:81], off
	global_load_dwordx4 v[0:3], v[80:81], off offset:112
	global_load_dwordx4 v[4:7], v[80:81], off offset:96
	global_load_dwordx4 v[8:11], v[80:81], off offset:80
	global_load_dwordx4 v[12:15], v[80:81], off offset:64
	v_and_b32_e32 v80, 0xffff0000, v56
	v_mul_f32_e32 v56, 0xbfb8aa3b, v79
	v_rcp_f32_e32 v45, v43
	s_nop 0
	v_mul_f32_e32 v43, v44, v45
	v_mul_f32_e32 v44, 0xbfb8aa3b, v71
	v_mul_f32_e32 v45, 0xbfb8aa3b, v58
	v_exp_f32_e32 v44, v44
	v_exp_f32_e32 v45, v45
	v_rcp_f32_e32 v67, v42
	s_nop 0
	v_mul_f32_e32 v42, v66, v67
	v_pk_add_f32 v[44:45], v[44:45], 1.0 op_sel_hi:[1,0]
	v_lshlrev_b32_e32 v83, 16, v54
	v_and_b32_e32 v54, 0xffff0000, v54
	v_lshlrev_b32_e32 v113, 16, v55
	v_and_b32_e32 v124, 0xffff0000, v55
	v_rcp_f32_e32 v59, v45
	s_nop 0
	v_mul_f32_e32 v45, v58, v59
	v_mul_f32_e32 v59, 0xbfb8aa3b, v57
	v_mul_f32_e32 v58, 0xbfb8aa3b, v77
	v_exp_f32_e32 v58, v58
	v_exp_f32_e32 v59, v59
	s_nop 0
	v_pk_add_f32 v[58:59], v[58:59], 1.0 op_sel_hi:[1,0]
	v_rcp_f32_e32 v66, v44
	s_nop 0
	v_mul_f32_e32 v44, v71, v66
	v_lshlrev_b32_e32 v88, 16, v53
	v_rcp_f32_e32 v66, v59
	s_nop 0
	v_mul_f32_e32 v57, v57, v66
	v_and_b32_e32 v53, 0xffff0000, v53
	v_exp_f32_e32 v66, v56
	v_mul_f32_e32 v56, 0xbfb8aa3b, v80
	v_exp_f32_e32 v67, v56
	v_rcp_f32_e32 v56, v58
	s_nop 0
	v_mul_f32_e32 v56, v77, v56
	v_lshlrev_b32_e32 v89, 16, v52
	ds_read2_b32 v[46:47], v158 offset0:6 offset1:7
	ds_read2_b32 v[60:61], v158 offset0:4 offset1:5
	ds_read2_b32 v[62:63], v158 offset0:2 offset1:3
	ds_read2_b32 v[64:65], v158 offset1:1
	v_pk_add_f32 v[66:67], v[66:67], 1.0 op_sel_hi:[1,0]
	ds_read2_b32 v[68:69], v158 offset0:14 offset1:15
	ds_read2_b32 v[70:71], v158 offset0:12 offset1:13
	ds_read2_b32 v[72:73], v158 offset0:10 offset1:11
	ds_read2_b32 v[74:75], v158 offset0:8 offset1:9
	s_waitcnt lgkmcnt(4)
	v_add_f32_e32 v32, 0, v64
	v_add_f32_e32 v32, v32, v65
	v_add_f32_e32 v32, v32, v62
	v_rcp_f32_e32 v59, v67
	s_nop 0
	v_mul_f32_e32 v59, v80, v59
	v_add_f32_e32 v32, v32, v63
	v_rcp_f32_e32 v58, v66
	s_nop 0
	v_mul_f32_e32 v58, v79, v58
	v_mul_f32_e32 v66, 0xbfb8aa3b, v78
	v_mul_f32_e32 v67, 0xbfb8aa3b, v76
	v_exp_f32_e32 v66, v66
	v_exp_f32_e32 v67, v67
	v_add_f32_e32 v32, v32, v60
	v_add_f32_e32 v32, v32, v61
	v_add_f32_e32 v32, v32, v46
	v_pk_add_f32 v[66:67], v[66:67], 1.0 op_sel_hi:[1,0]
	v_add_f32_e32 v32, v32, v47
	s_waitcnt lgkmcnt(0)
	v_add_f32_e32 v32, v32, v74
	v_add_f32_e32 v32, v32, v75
	v_add_f32_e32 v32, v32, v72
	v_rcp_f32_e32 v77, v67
	s_nop 0
	v_mul_f32_e32 v67, v76, v77
	v_mul_f32_e32 v76, 0xbfb8aa3b, v83
	v_mul_f32_e32 v77, 0xbfb8aa3b, v54
	v_exp_f32_e32 v76, v76
	v_exp_f32_e32 v77, v77
	v_rcp_f32_e32 v79, v66
	s_nop 0
	v_mul_f32_e32 v66, v78, v79
	v_pk_add_f32 v[76:77], v[76:77], 1.0 op_sel_hi:[1,0]
	v_add_f32_e32 v32, v32, v73
	v_add_f32_e32 v32, v32, v70
	v_add_f32_e32 v32, v32, v71
	v_add_f32_e32 v32, v32, v68
	v_mul_f32_e32 v78, 0xbfb8aa3b, v88
	v_mul_f32_e32 v79, 0xbfb8aa3b, v53
	v_rcp_f32_e32 v55, v77
	s_nop 0
	v_mul_f32_e32 v55, v54, v55
	v_exp_f32_e32 v78, v78
	v_exp_f32_e32 v79, v79
	s_nop 0
	v_pk_add_f32 v[78:79], v[78:79], 1.0 op_sel_hi:[1,0]
	v_rcp_f32_e32 v54, v76
	s_nop 0
	v_mul_f32_e32 v54, v83, v54
	v_add_f32_e32 v32, v32, v69
	v_rcp_f32_e32 v77, v79
	s_nop 0
	v_mul_f32_e32 v77, v53, v77
	s_mov_b32 s37, 0
	v_and_b32_e32 v79, 0xffff0000, v52
	v_mul_f32_e32 v52, 0xbfb8aa3b, v89
	v_mul_f32_e32 v53, 0xbfb8aa3b, v79
	v_exp_f32_e32 v52, v52
	v_exp_f32_e32 v53, v53
	v_rcp_f32_e32 v76, v78
	s_nop 0
	v_mul_f32_e32 v76, v88, v76
	ds_read2_b32 v[80:81], v158 offset0:22 offset1:23
	ds_read2_b32 v[82:83], v158 offset0:20 offset1:21
	ds_read2_b32 v[84:85], v158 offset0:18 offset1:19
	ds_read2_b32 v[86:87], v158 offset0:16 offset1:17
	v_lshl_add_u64 v[34:35], v[34:35], 0, s[36:37]
	v_pk_add_f32 v[52:53], v[52:53], 1.0 op_sel_hi:[1,0]
	v_mov_b32_e32 v115, v33
	s_waitcnt lgkmcnt(0)
	v_add_f32_e32 v32, v32, v86
	v_add_f32_e32 v32, v32, v87
	v_add_f32_e32 v32, v32, v84
	v_rcp_f32_e32 v78, v53
	s_nop 0
	v_mul_f32_e32 v79, v79, v78
	v_add_f32_e32 v32, v32, v85
	v_rcp_f32_e32 v78, v52
	s_nop 0
	v_mul_f32_e32 v78, v89, v78
	v_mul_f32_e32 v52, 0xbfb8aa3b, v113
	v_mul_f32_e32 v53, 0xbfb8aa3b, v124
	v_exp_f32_e32 v52, v52
	v_exp_f32_e32 v53, v53
	v_add_f32_e32 v32, v32, v82
	v_add_f32_e32 v32, v32, v83
	v_add_f32_e32 v32, v32, v80
	v_pk_add_f32 v[88:89], v[52:53], 1.0 op_sel_hi:[1,0]
	ds_read2_b32 v[90:91], v158 offset0:30 offset1:31
	ds_read2_b32 v[52:53], v158 offset0:28 offset1:29
	ds_read2_b32 v[92:93], v158 offset0:26 offset1:27
	ds_read2_b32 v[94:95], v158 offset0:24 offset1:25
	v_add_f32_e32 v32, v32, v81
	s_waitcnt lgkmcnt(0)
	v_add_f32_e32 v32, v32, v94
	v_add_f32_e32 v32, v32, v95
	v_add_f32_e32 v32, v32, v92
	v_add_f32_e32 v32, v32, v93
	v_add_f32_e32 v32, v32, v52
	v_add_f32_e32 v32, v32, v53
	v_add_f32_e32 v32, v32, v90
	v_add_f32_e32 v32, v32, v91
	ds_bpermute_b32 v97, v157, v32
	s_waitcnt lgkmcnt(0)
	v_add_f32_e32 v32, v32, v97
	ds_bpermute_b32 v97, v156, v32
	v_lshl_add_u64 v[34:35], v[34:35], 0, v[114:115]
	s_waitcnt lgkmcnt(0)
	v_add_f32_e32 v32, v32, v97
	v_mul_f32_e32 v32, 0x3c000000, v32
	v_pk_add_f32 v[64:65], v[64:65], v[32:33] op_sel_hi:[1,0] neg_lo:[0,1] neg_hi:[0,1]
	v_pk_add_f32 v[62:63], v[62:63], v[32:33] op_sel_hi:[1,0] neg_lo:[0,1] neg_hi:[0,1]
	v_pk_mul_f32 v[96:97], v[64:65], v[64:65]
	v_pk_mul_f32 v[98:99], v[62:63], v[62:63]
	v_pk_add_f32 v[100:101], v[60:61], v[32:33] op_sel_hi:[1,0] neg_lo:[0,1] neg_hi:[0,1]
	v_pk_add_f32 v[104:105], v[46:47], v[32:33] op_sel_hi:[1,0] neg_lo:[0,1] neg_hi:[0,1]
	v_pk_add_f32 v[74:75], v[74:75], v[32:33] op_sel_hi:[1,0] neg_lo:[0,1] neg_hi:[0,1]
	v_pk_add_f32 v[72:73], v[72:73], v[32:33] op_sel_hi:[1,0] neg_lo:[0,1] neg_hi:[0,1]
	v_pk_add_f32 v[70:71], v[70:71], v[32:33] op_sel_hi:[1,0] neg_lo:[0,1] neg_hi:[0,1]
	v_pk_add_f32 v[68:69], v[68:69], v[32:33] op_sel_hi:[1,0] neg_lo:[0,1] neg_hi:[0,1]
	v_pk_add_f32 v[86:87], v[86:87], v[32:33] op_sel_hi:[1,0] neg_lo:[0,1] neg_hi:[0,1]
	v_pk_add_f32 v[84:85], v[84:85], v[32:33] op_sel_hi:[1,0] neg_lo:[0,1] neg_hi:[0,1]
	v_pk_add_f32 v[82:83], v[82:83], v[32:33] op_sel_hi:[1,0] neg_lo:[0,1] neg_hi:[0,1]
	v_pk_add_f32 v[80:81], v[80:81], v[32:33] op_sel_hi:[1,0] neg_lo:[0,1] neg_hi:[0,1]
	v_pk_add_f32 v[94:95], v[94:95], v[32:33] op_sel_hi:[1,0] neg_lo:[0,1] neg_hi:[0,1]
	v_pk_add_f32 v[60:61], v[92:93], v[32:33] op_sel_hi:[1,0] neg_lo:[0,1] neg_hi:[0,1]
	v_pk_add_f32 v[52:53], v[52:53], v[32:33] op_sel_hi:[1,0] neg_lo:[0,1] neg_hi:[0,1]
	v_pk_add_f32 v[46:47], v[90:91], v[32:33] op_sel_hi:[1,0] neg_lo:[0,1] neg_hi:[0,1]
	v_add_f32_e32 v32, v96, v97
	v_add_f32_e32 v32, v98, v32
	v_pk_mul_f32 v[102:103], v[100:101], v[100:101]
	v_add_f32_e32 v32, v99, v32
	v_add_f32_e32 v32, v102, v32
	v_pk_mul_f32 v[106:107], v[104:105], v[104:105]
	v_add_f32_e32 v32, v103, v32
	v_add_f32_e32 v32, v106, v32
	v_pk_mul_f32 v[108:109], v[74:75], v[74:75]
	v_add_f32_e32 v32, v107, v32
	v_add_f32_e32 v32, v108, v32
	v_pk_mul_f32 v[110:111], v[72:73], v[72:73]
	v_add_f32_e32 v32, v109, v32
	v_add_f32_e32 v32, v110, v32
	v_pk_mul_f32 v[114:115], v[70:71], v[70:71]
	v_add_f32_e32 v32, v111, v32
	v_add_f32_e32 v32, v114, v32
	v_pk_mul_f32 v[116:117], v[68:69], v[68:69]
	v_add_f32_e32 v32, v115, v32
	v_add_f32_e32 v32, v116, v32
	v_pk_mul_f32 v[118:119], v[86:87], v[86:87]
	v_add_f32_e32 v32, v117, v32
	v_add_f32_e32 v32, v118, v32
	v_pk_mul_f32 v[120:121], v[84:85], v[84:85]
	v_add_f32_e32 v32, v119, v32
	v_add_f32_e32 v32, v120, v32
	v_pk_mul_f32 v[122:123], v[82:83], v[82:83]
	v_add_f32_e32 v32, v121, v32
	v_add_f32_e32 v32, v122, v32
	v_pk_mul_f32 v[126:127], v[80:81], v[80:81]
	v_add_f32_e32 v32, v123, v32
	v_add_f32_e32 v32, v126, v32
	v_pk_mul_f32 v[128:129], v[94:95], v[94:95]
	v_add_f32_e32 v32, v127, v32
	v_add_f32_e32 v32, v128, v32
	v_pk_mul_f32 v[92:93], v[60:61], v[60:61]
	v_add_f32_e32 v32, v129, v32
	v_add_f32_e32 v32, v92, v32
	v_pk_mul_f32 v[130:131], v[52:53], v[52:53]
	v_add_f32_e32 v32, v93, v32
	v_add_f32_e32 v32, v130, v32
	v_pk_mul_f32 v[90:91], v[46:47], v[46:47]
	v_add_f32_e32 v32, v131, v32
	v_add_f32_e32 v32, v90, v32
	v_add_f32_e32 v32, v91, v32
	ds_bpermute_b32 v90, v157, v32
	s_mov_b32 s0, 0xf800000
	v_rcp_f32_e32 v91, v89
	s_nop 0
	v_mul_f32_e32 v89, v124, v91
	s_waitcnt lgkmcnt(0)
	v_add_f32_e32 v32, v32, v90
	ds_bpermute_b32 v90, v156, v32
	s_waitcnt lgkmcnt(0)
	v_add_f32_e32 v32, v32, v90
	v_mov_b32_e32 v90, 0x358637bd
	v_fmac_f32_e32 v90, 0x3c000000, v32
	v_mul_f32_e32 v32, 0x4f800000, v90
	v_cmp_gt_f32_e64 s[0:1], s0, v90
	s_nop 1
	v_cndmask_b32_e64 v32, v90, v32, s[0:1]
	v_sqrt_f32_e32 v90, v32
	v_readlane_b32 s5, v254, 1
	v_add_u32_e32 v93, -1, v90
	v_fma_f32 v96, -v93, v90, v32
	v_cmp_ge_f32_e64 s[4:5], 0, v96
	v_add_u32_e32 v96, 1, v90
	s_nop 1
	v_cndmask_b32_e64 v93, v90, v93, s[4:5]
	v_fma_f32 v90, -v96, v90, v32
	v_cmp_lt_f32_e64 s[4:5], 0, v90
	v_rcp_f32_e32 v91, v88
	s_nop 0
	v_mul_f32_e32 v88, v113, v91
	s_movk_i32 s2, 0x37ff
	v_cndmask_b32_e64 v90, v93, v96, s[4:5]
	v_mul_f32_e32 v93, 0x37800000, v90
	v_cndmask_b32_e64 v90, v90, v93, s[0:1]
	v_mov_b32_e32 v93, 0x260
	v_cmp_class_f32_e64 s[0:1], v32, v93
	s_nop 1
	v_cndmask_b32_e64 v32, v90, v32, s[0:1]
	v_rcp_f32_e32 v32, v32
	s_nop 0
	v_pk_mul_f32 v[64:65], v[64:65], v[32:33] op_sel_hi:[1,0]
	s_waitcnt vmcnt(4)
	v_pk_mul_f32 v[28:29], v[28:29], v[64:65]
	s_nop 0
	v_pk_mul_f32 v[28:29], v[40:41], v[28:29]
	v_pk_mul_f32 v[40:41], v[62:63], v[32:33] op_sel_hi:[1,0]
	s_nop 0
	v_pk_mul_f32 v[30:31], v[30:31], v[40:41]
	s_nop 0
	v_pk_mul_f32 v[30:31], v[38:39], v[30:31]
	v_pk_mul_f32 v[38:39], v[100:101], v[32:33] op_sel_hi:[1,0]
	s_nop 0
	v_pk_mul_f32 v[24:25], v[24:25], v[38:39]
	s_nop 0
	v_pk_mul_f32 v[36:37], v[36:37], v[24:25]
	v_pk_mul_f32 v[24:25], v[104:105], v[32:33] op_sel_hi:[1,0]
	s_nop 0
	v_pk_mul_f32 v[24:25], v[26:27], v[24:25]
	v_cvt_pk_bf16_f32 v26, v36, v37
	v_pk_mul_f32 v[38:39], v[42:43], v[24:25]
	v_cvt_pk_bf16_f32 v24, v28, v29
	v_cvt_pk_bf16_f32 v25, v30, v31
	v_cvt_pk_bf16_f32 v27, v38, v39
	global_store_dwordx4 v[34:35], v[24:27], off
	s_nop 1
	v_pk_mul_f32 v[24:25], v[74:75], v[32:33] op_sel_hi:[1,0]
	s_nop 0
	v_pk_mul_f32 v[20:21], v[20:21], v[24:25]
	v_pk_mul_f32 v[24:25], v[72:73], v[32:33] op_sel_hi:[1,0]
	v_pk_mul_f32 v[20:21], v[58:59], v[20:21]
	v_pk_mul_f32 v[22:23], v[22:23], v[24:25]
	v_pk_mul_f32 v[24:25], v[70:71], v[32:33] op_sel_hi:[1,0]
	v_pk_mul_f32 v[22:23], v[56:57], v[22:23]
	v_pk_mul_f32 v[16:17], v[16:17], v[24:25]
	s_nop 0
	v_pk_mul_f32 v[24:25], v[44:45], v[16:17]
	v_pk_mul_f32 v[16:17], v[68:69], v[32:33] op_sel_hi:[1,0]
	s_nop 0
	v_pk_mul_f32 v[16:17], v[18:19], v[16:17]
	v_cvt_pk_bf16_f32 v18, v24, v25
	v_pk_mul_f32 v[26:27], v[66:67], v[16:17]
	v_cvt_pk_bf16_f32 v16, v20, v21
	v_cvt_pk_bf16_f32 v17, v22, v23
	v_cvt_pk_bf16_f32 v19, v26, v27
	global_store_dwordx4 v[34:35], v[16:19], off offset:16
	v_lshlrev_b32_e32 v20, 16, v48
	v_and_b32_e32 v21, 0xffff0000, v48
	v_pk_mul_f32 v[16:17], v[86:87], v[32:33] op_sel_hi:[1,0]
	s_waitcnt vmcnt(2)
	v_pk_mul_f32 v[12:13], v[12:13], v[16:17]
	v_pk_mul_f32 v[16:17], v[84:85], v[32:33] op_sel_hi:[1,0]
	v_pk_mul_f32 v[12:13], v[78:79], v[12:13]
	v_pk_mul_f32 v[14:15], v[14:15], v[16:17]
	v_pk_mul_f32 v[16:17], v[82:83], v[32:33] op_sel_hi:[1,0]
	v_pk_mul_f32 v[14:15], v[76:77], v[14:15]
	v_pk_mul_f32 v[8:9], v[8:9], v[16:17]
	s_nop 0
	v_pk_mul_f32 v[16:17], v[54:55], v[8:9]
	v_pk_mul_f32 v[8:9], v[80:81], v[32:33] op_sel_hi:[1,0]
	s_nop 0
	v_pk_mul_f32 v[8:9], v[10:11], v[8:9]
	v_mul_f32_e32 v10, 0xbfb8aa3b, v20
	v_mul_f32_e32 v11, 0xbfb8aa3b, v21
	v_exp_f32_e32 v10, v10
	v_exp_f32_e32 v11, v11
	v_pk_mul_f32 v[18:19], v[88:89], v[8:9]
	v_cvt_pk_bf16_f32 v8, v12, v13
	v_cvt_pk_bf16_f32 v9, v14, v15
	v_pk_add_f32 v[12:13], v[10:11], 1.0 op_sel_hi:[1,0]
	v_cvt_pk_bf16_f32 v10, v16, v17
	v_cvt_pk_bf16_f32 v11, v18, v19
	global_store_dwordx4 v[34:35], v[8:11], off offset:32
	v_and_b32_e32 v16, 0xffff0000, v49
	s_nop 0
	v_rcp_f32_e32 v9, v13
	s_nop 0
	v_mul_f32_e32 v9, v21, v9
	v_lshlrev_b32_e32 v15, 16, v49
	v_mul_f32_e32 v10, 0xbfb8aa3b, v15
	v_mul_f32_e32 v11, 0xbfb8aa3b, v16
	v_exp_f32_e32 v10, v10
	v_exp_f32_e32 v11, v11
	v_rcp_f32_e32 v8, v12
	s_nop 0
	v_mul_f32_e32 v8, v20, v8
	v_pk_mul_f32 v[12:13], v[94:95], v[32:33] op_sel_hi:[1,0]
	v_pk_add_f32 v[10:11], v[10:11], 1.0 op_sel_hi:[1,0]
	v_pk_mul_f32 v[4:5], v[4:5], v[12:13]
	v_pk_mul_f32 v[4:5], v[8:9], v[4:5]
	v_rcp_f32_e32 v9, v11
	s_nop 0
	v_mul_f32_e32 v9, v16, v9
	v_lshlrev_b32_e32 v16, 16, v50
	v_and_b32_e32 v17, 0xffff0000, v50
	v_mul_f32_e32 v12, 0xbfb8aa3b, v16
	v_mul_f32_e32 v13, 0xbfb8aa3b, v17
	v_exp_f32_e32 v12, v12
	v_exp_f32_e32 v13, v13
	v_rcp_f32_e32 v8, v10
	s_nop 0
	v_mul_f32_e32 v8, v15, v8
	v_pk_add_f32 v[10:11], v[12:13], 1.0 op_sel_hi:[1,0]
	s_nop 0
	v_pk_mul_f32 v[12:13], v[60:61], v[32:33] op_sel_hi:[1,0]
	s_nop 0
	v_pk_mul_f32 v[6:7], v[6:7], v[12:13]
	s_nop 0
	v_pk_mul_f32 v[6:7], v[8:9], v[6:7]
	v_rcp_f32_e32 v9, v11
	s_nop 0
	v_mul_f32_e32 v9, v17, v9
	v_lshlrev_b32_e32 v15, 16, v51
	v_and_b32_e32 v17, 0xffff0000, v51
	v_mul_f32_e32 v12, 0xbfb8aa3b, v15
	v_mul_f32_e32 v13, 0xbfb8aa3b, v17
	v_exp_f32_e32 v12, v12
	v_exp_f32_e32 v13, v13
	v_rcp_f32_e32 v8, v10
	s_nop 0
	v_mul_f32_e32 v8, v16, v8
	v_pk_add_f32 v[10:11], v[12:13], 1.0 op_sel_hi:[1,0]
	s_nop 0
	v_pk_mul_f32 v[12:13], v[52:53], v[32:33] op_sel_hi:[1,0]
	s_nop 0
	v_pk_mul_f32 v[0:1], v[0:1], v[12:13]
	s_nop 0
	v_pk_mul_f32 v[8:9], v[8:9], v[0:1]
	v_rcp_f32_e32 v1, v11
	s_nop 0
	v_mul_f32_e32 v1, v17, v1
	v_rcp_f32_e32 v0, v10
	s_nop 0
	v_mul_f32_e32 v0, v15, v0
	v_pk_mul_f32 v[10:11], v[46:47], v[32:33] op_sel_hi:[1,0]
	s_mov_b64 s[0:1], 0x3300000
	v_pk_mul_f32 v[2:3], v[2:3], v[10:11]
	s_nop 0
	v_pk_mul_f32 v[10:11], v[0:1], v[2:3]
	v_cvt_pk_bf16_f32 v0, v4, v5
	v_cvt_pk_bf16_f32 v1, v6, v7
	v_cvt_pk_bf16_f32 v2, v8, v9
	v_cvt_pk_bf16_f32 v3, v10, v11
	global_store_dwordx4 v[34:35], v[0:3], off offset:48
	v_lshl_add_u32 v5, s52, 9, v226
	s_waitcnt lgkmcnt(0)
	s_barrier
	s_cmp_eq_u32 s99, 2
	s_cbranch_scc1 .Lcomb_end
.Lcomb_start:
	s_lshr_b32 s0, s88, 5
	s_lshl_b32 s1, s0, 3
	s_add_i32 s1, s1, s53
	s_lshl_b32 s2, s1, 8
	s_lshl_b32 s3, s52, 3
	s_add_i32 s2, s2, s3
	v_readlane_b32 s8, v254, 2
	v_readlane_b32 s9, v254, 3
	v_lshrrev_b32_e32 v22, 6, v226
	v_add_u32_e32 v23, s2, v22
	v_and_b32_e32 v32, 63, v226
	v_lshlrev_b32_e32 v32, 4, v32
	v_bfe_u32 v33, v226, 3, 3
	v_lshlrev_b32_e32 v33, 2, v33
	v_lshl_add_u32 v0, v23, 5, v33
	v_add_u32_e32 v0, 0x3300000, v0
	v_add_u32_e32 v1, 0x1000, v0
	v_add_u32_e32 v2, 0x80000, v0
	v_add_u32_e32 v3, 0x81000, v0
	v_add_u32_e32 v4, 0x100000, v0
	v_add_u32_e32 v5, 0x101000, v0
	v_lshl_add_u32 v6, v23, 10, v32
	v_add_u32_e32 v6, 0xb500000, v6
	v_add_u32_e32 v7, s3, v22
	v_lshl_add_u32 v7, v7, 11, v32
	s_lshl_b32 s2, s1, 20
	s_add_u32 s8, s8, s2
	s_addc_u32 s9, s9, 0
	global_load_dword v60, v0, s[96:97]
	global_load_dword v61, v2, s[96:97]
	global_load_dword v62, v4, s[96:97]
	global_load_dwordx4 v[48:51], v6, s[96:97]
	v_add_u32_e32 v8, 0x1000000, v6
	global_load_dwordx4 v[52:55], v8, s[96:97]
	v_add_u32_e32 v8, 0x2000000, v6
	global_load_dwordx4 v[56:59], v8, s[96:97]
	global_load_dword v76, v0, s[96:97] offset:1024
	global_load_dword v77, v2, s[96:97] offset:1024
	global_load_dword v78, v4, s[96:97] offset:1024
	v_add_u32_e32 v8, 0x8000, v6
	global_load_dwordx4 v[64:67], v8, s[96:97]
	v_add_u32_e32 v8, 0x1008000, v6
	global_load_dwordx4 v[68:71], v8, s[96:97]
	v_add_u32_e32 v8, 0x2008000, v6
	global_load_dwordx4 v[72:75], v8, s[96:97]
	global_load_dword v92, v0, s[96:97] offset:2048
	global_load_dword v93, v2, s[96:97] offset:2048
	global_load_dword v94, v4, s[96:97] offset:2048
	v_add_u32_e32 v8, 0x10000, v6
	global_load_dwordx4 v[80:83], v8, s[96:97]
	v_add_u32_e32 v8, 0x1010000, v6
	global_load_dwordx4 v[84:87], v8, s[96:97]
	v_add_u32_e32 v8, 0x2010000, v6
	global_load_dwordx4 v[88:91], v8, s[96:97]
	global_load_dword v108, v0, s[96:97] offset:3072
	global_load_dword v109, v2, s[96:97] offset:3072
	global_load_dword v110, v4, s[96:97] offset:3072
	v_add_u32_e32 v8, 0x18000, v6
	global_load_dwordx4 v[96:99], v8, s[96:97]
	v_add_u32_e32 v8, 0x1018000, v6
	global_load_dwordx4 v[100:103], v8, s[96:97]
	v_add_u32_e32 v8, 0x2018000, v6
	global_load_dwordx4 v[104:107], v8, s[96:97]
	global_load_dword v140, v1, s[96:97]
	global_load_dword v141, v3, s[96:97]
	global_load_dword v142, v5, s[96:97]
	v_add_u32_e32 v8, 0x20000, v6
	global_load_dwordx4 v[128:131], v8, s[96:97]
	v_add_u32_e32 v8, 0x1020000, v6
	global_load_dwordx4 v[132:135], v8, s[96:97]
	v_add_u32_e32 v8, 0x2020000, v6
	global_load_dwordx4 v[136:139], v8, s[96:97]
	global_load_dword v164, v1, s[96:97] offset:1024
	global_load_dword v165, v3, s[96:97] offset:1024
	global_load_dword v166, v5, s[96:97] offset:1024
	v_add_u32_e32 v8, 0x28000, v6
	global_load_dwordx4 v[152:155], v8, s[96:97]
	v_add_u32_e32 v8, 0x1028000, v6
	global_load_dwordx4 v[156:159], v8, s[96:97]
	v_add_u32_e32 v8, 0x2028000, v6
	global_load_dwordx4 v[160:163], v8, s[96:97]
	global_load_dword v218, v1, s[96:97] offset:2048
	global_load_dword v219, v3, s[96:97] offset:2048
	global_load_dword v220, v5, s[96:97] offset:2048
	v_add_u32_e32 v8, 0x30000, v6
	global_load_dwordx4 v[206:209], v8, s[96:97]
	v_add_u32_e32 v8, 0x1030000, v6
	global_load_dwordx4 v[210:213], v8, s[96:97]
	v_add_u32_e32 v8, 0x2030000, v6
	global_load_dwordx4 v[214:217], v8, s[96:97]
	global_load_dword v244, v1, s[96:97] offset:3072
	global_load_dword v245, v3, s[96:97] offset:3072
	global_load_dword v246, v5, s[96:97] offset:3072
	v_add_u32_e32 v8, 0x38000, v6
	global_load_dwordx4 v[232:235], v8, s[96:97]
	v_add_u32_e32 v8, 0x1038000, v6
	global_load_dwordx4 v[236:239], v8, s[96:97]
	v_add_u32_e32 v8, 0x2038000, v6
	global_load_dwordx4 v[240:243], v8, s[96:97]
	s_waitcnt vmcnt(42)
	v_max3_f32 v5, v60, v61, v62
	v_sub_f32_e32 v9, v60, v5
	v_sub_f32_e32 v40, v61, v5
	v_and_b32_e32 v27, 0xffff0000, v49
	v_lshlrev_b32_e32 v28, 16, v49
	v_sub_f32_e32 v5, v62, v5
	v_lshlrev_b32_e32 v24, 16, v52
	v_and_b32_e32 v11, 0xffff0000, v52
	v_lshlrev_b32_e32 v38, 16, v56
	v_and_b32_e32 v39, 0xffff0000, v56
	v_lshlrev_b32_e32 v26, 16, v53
	v_and_b32_e32 v29, 0xffff0000, v53
	v_lshlrev_b32_e32 v14, 16, v57
	v_and_b32_e32 v15, 0xffff0000, v57
	v_lshlrev_b32_e32 v18, 16, v58
	v_and_b32_e32 v19, 0xffff0000, v58
	v_mul_f32_e32 v9, 0x3fb8aa3b, v9
	v_mul_f32_e32 v20, 0x3fb8aa3b, v40
	v_and_b32_e32 v35, 0xffff0000, v51
	v_lshlrev_b32_e32 v36, 16, v51
	v_lshlrev_b32_e32 v30, 16, v54
	v_and_b32_e32 v13, 0xffff0000, v54
	v_lshlrev_b32_e32 v34, 16, v55
	v_and_b32_e32 v37, 0xffff0000, v55
	v_lshlrev_b32_e32 v16, 16, v59
	v_and_b32_e32 v17, 0xffff0000, v59
	v_mul_f32_e32 v5, 0x3fb8aa3b, v5
	v_exp_f32_e32 v21, v9
	v_exp_f32_e32 v20, v20
	v_exp_f32_e32 v5, v5
	v_and_b32_e32 v25, 0xffff0000, v48
	v_lshlrev_b32_e32 v10, 16, v48
	v_add_f32_e32 v9, v21, v20
	v_add_f32_e32 v9, v5, v9
	v_and_b32_e32 v31, 0xffff0000, v50
	v_rcp_f32_e32 v40, v9
	s_nop 0
	v_lshlrev_b32_e32 v12, 16, v50
	v_pk_mul_f32 v[20:21], v[20:21], v[40:41] op_sel_hi:[1,0]
	v_mul_f32_e32 v42, v5, v40
	v_pk_mul_f32 v[10:11], v[20:21], v[10:11] op_sel:[1,0] op_sel_hi:[0,1]
	v_pk_mul_f32 v[28:29], v[20:21], v[28:29] op_sel:[1,0] op_sel_hi:[0,1]
	v_pk_mul_f32 v[12:13], v[20:21], v[12:13] op_sel:[1,0] op_sel_hi:[0,1]
	v_pk_mul_f32 v[36:37], v[20:21], v[36:37] op_sel:[1,0] op_sel_hi:[0,1]
	v_pk_fma_f32 v[10:11], v[20:21], v[24:25], v[10:11]
	v_pk_fma_f32 v[24:25], v[20:21], v[26:27], v[28:29]
	v_pk_fma_f32 v[12:13], v[20:21], v[30:31], v[12:13]
	v_pk_fma_f32 v[20:21], v[20:21], v[34:35], v[36:37]
	v_pk_fma_f32 v[10:11], v[42:43], v[38:39], v[10:11] op_sel_hi:[0,1,1]
	v_pk_fma_f32 v[14:15], v[42:43], v[14:15], v[24:25] op_sel_hi:[0,1,1]
	v_pk_fma_f32 v[12:13], v[42:43], v[18:19], v[12:13] op_sel_hi:[0,1,1]
	v_pk_fma_f32 v[16:17], v[42:43], v[16:17], v[20:21] op_sel_hi:[0,1,1]
	v_cvt_pk_bf16_f32 v10, v10, v11
	v_cvt_pk_bf16_f32 v11, v14, v15
	v_cvt_pk_bf16_f32 v12, v12, v13
	v_cvt_pk_bf16_f32 v13, v16, v17
	global_store_dwordx4 v7, v[10:13], s[8:9] offset:1024
	s_waitcnt vmcnt(37)
	v_max3_f32 v5, v76, v77, v78
	v_sub_f32_e32 v9, v76, v5
	v_sub_f32_e32 v40, v77, v5
	v_and_b32_e32 v27, 0xffff0000, v65
	v_lshlrev_b32_e32 v28, 16, v65
	v_sub_f32_e32 v5, v78, v5
	v_lshlrev_b32_e32 v24, 16, v68
	v_and_b32_e32 v11, 0xffff0000, v68
	v_lshlrev_b32_e32 v38, 16, v72
	v_and_b32_e32 v39, 0xffff0000, v72
	v_lshlrev_b32_e32 v26, 16, v69
	v_and_b32_e32 v29, 0xffff0000, v69
	v_lshlrev_b32_e32 v14, 16, v73
	v_and_b32_e32 v15, 0xffff0000, v73
	v_lshlrev_b32_e32 v18, 16, v74
	v_and_b32_e32 v19, 0xffff0000, v74
	v_mul_f32_e32 v9, 0x3fb8aa3b, v9
	v_mul_f32_e32 v20, 0x3fb8aa3b, v40
	v_and_b32_e32 v35, 0xffff0000, v67
	v_lshlrev_b32_e32 v36, 16, v67
	v_lshlrev_b32_e32 v30, 16, v70
	v_and_b32_e32 v13, 0xffff0000, v70
	v_lshlrev_b32_e32 v34, 16, v71
	v_and_b32_e32 v37, 0xffff0000, v71
	v_lshlrev_b32_e32 v16, 16, v75
	v_and_b32_e32 v17, 0xffff0000, v75
	v_mul_f32_e32 v5, 0x3fb8aa3b, v5
	v_exp_f32_e32 v21, v9
	v_exp_f32_e32 v20, v20
	v_exp_f32_e32 v5, v5
	v_and_b32_e32 v25, 0xffff0000, v64
	v_lshlrev_b32_e32 v10, 16, v64
	v_add_f32_e32 v9, v21, v20
	v_add_f32_e32 v9, v5, v9
	v_and_b32_e32 v31, 0xffff0000, v66
	v_rcp_f32_e32 v40, v9
	s_nop 0
	v_lshlrev_b32_e32 v12, 16, v66
	v_pk_mul_f32 v[20:21], v[20:21], v[40:41] op_sel_hi:[1,0]
	v_mul_f32_e32 v42, v5, v40
	v_pk_mul_f32 v[10:11], v[20:21], v[10:11] op_sel:[1,0] op_sel_hi:[0,1]
	v_pk_mul_f32 v[28:29], v[20:21], v[28:29] op_sel:[1,0] op_sel_hi:[0,1]
	v_pk_mul_f32 v[12:13], v[20:21], v[12:13] op_sel:[1,0] op_sel_hi:[0,1]
	v_pk_mul_f32 v[36:37], v[20:21], v[36:37] op_sel:[1,0] op_sel_hi:[0,1]
	v_pk_fma_f32 v[10:11], v[20:21], v[24:25], v[10:11]
	v_pk_fma_f32 v[24:25], v[20:21], v[26:27], v[28:29]
	v_pk_fma_f32 v[12:13], v[20:21], v[30:31], v[12:13]
	v_pk_fma_f32 v[20:21], v[20:21], v[34:35], v[36:37]
	v_pk_fma_f32 v[10:11], v[42:43], v[38:39], v[10:11] op_sel_hi:[0,1,1]
	v_pk_fma_f32 v[14:15], v[42:43], v[14:15], v[24:25] op_sel_hi:[0,1,1]
	v_pk_fma_f32 v[12:13], v[42:43], v[18:19], v[12:13] op_sel_hi:[0,1,1]
	v_pk_fma_f32 v[16:17], v[42:43], v[16:17], v[20:21] op_sel_hi:[0,1,1]
	v_cvt_pk_bf16_f32 v10, v10, v11
	v_cvt_pk_bf16_f32 v11, v14, v15
	v_cvt_pk_bf16_f32 v12, v12, v13
	v_cvt_pk_bf16_f32 v13, v16, v17
	v_add_u32_e32 v8, 0x10000, v7
	global_store_dwordx4 v8, v[10:13], s[8:9] offset:1024
	s_waitcnt vmcnt(32)
	v_max3_f32 v5, v92, v93, v94
	v_sub_f32_e32 v9, v92, v5
	v_sub_f32_e32 v40, v93, v5
	v_and_b32_e32 v27, 0xffff0000, v81
	v_lshlrev_b32_e32 v28, 16, v81
	v_sub_f32_e32 v5, v94, v5
	v_lshlrev_b32_e32 v24, 16, v84
	v_and_b32_e32 v11, 0xffff0000, v84
	v_lshlrev_b32_e32 v38, 16, v88
	v_and_b32_e32 v39, 0xffff0000, v88
	v_lshlrev_b32_e32 v26, 16, v85
	v_and_b32_e32 v29, 0xffff0000, v85
	v_lshlrev_b32_e32 v14, 16, v89
	v_and_b32_e32 v15, 0xffff0000, v89
	v_lshlrev_b32_e32 v18, 16, v90
	v_and_b32_e32 v19, 0xffff0000, v90
	v_mul_f32_e32 v9, 0x3fb8aa3b, v9
	v_mul_f32_e32 v20, 0x3fb8aa3b, v40
	v_and_b32_e32 v35, 0xffff0000, v83
	v_lshlrev_b32_e32 v36, 16, v83
	v_lshlrev_b32_e32 v30, 16, v86
	v_and_b32_e32 v13, 0xffff0000, v86
	v_lshlrev_b32_e32 v34, 16, v87
	v_and_b32_e32 v37, 0xffff0000, v87
	v_lshlrev_b32_e32 v16, 16, v91
	v_and_b32_e32 v17, 0xffff0000, v91
	v_mul_f32_e32 v5, 0x3fb8aa3b, v5
	v_exp_f32_e32 v21, v9
	v_exp_f32_e32 v20, v20
	v_exp_f32_e32 v5, v5
	v_and_b32_e32 v25, 0xffff0000, v80
	v_lshlrev_b32_e32 v10, 16, v80
	v_add_f32_e32 v9, v21, v20
	v_add_f32_e32 v9, v5, v9
	v_and_b32_e32 v31, 0xffff0000, v82
	v_rcp_f32_e32 v40, v9
	s_nop 0
	v_lshlrev_b32_e32 v12, 16, v82
	v_pk_mul_f32 v[20:21], v[20:21], v[40:41] op_sel_hi:[1,0]
	v_mul_f32_e32 v42, v5, v40
	v_pk_mul_f32 v[10:11], v[20:21], v[10:11] op_sel:[1,0] op_sel_hi:[0,1]
	v_pk_mul_f32 v[28:29], v[20:21], v[28:29] op_sel:[1,0] op_sel_hi:[0,1]
	v_pk_mul_f32 v[12:13], v[20:21], v[12:13] op_sel:[1,0] op_sel_hi:[0,1]
	v_pk_mul_f32 v[36:37], v[20:21], v[36:37] op_sel:[1,0] op_sel_hi:[0,1]
	v_pk_fma_f32 v[10:11], v[20:21], v[24:25], v[10:11]
	v_pk_fma_f32 v[24:25], v[20:21], v[26:27], v[28:29]
	v_pk_fma_f32 v[12:13], v[20:21], v[30:31], v[12:13]
	v_pk_fma_f32 v[20:21], v[20:21], v[34:35], v[36:37]
	v_pk_fma_f32 v[10:11], v[42:43], v[38:39], v[10:11] op_sel_hi:[0,1,1]
	v_pk_fma_f32 v[14:15], v[42:43], v[14:15], v[24:25] op_sel_hi:[0,1,1]
	v_pk_fma_f32 v[12:13], v[42:43], v[18:19], v[12:13] op_sel_hi:[0,1,1]
	v_pk_fma_f32 v[16:17], v[42:43], v[16:17], v[20:21] op_sel_hi:[0,1,1]
	v_cvt_pk_bf16_f32 v10, v10, v11
	v_cvt_pk_bf16_f32 v11, v14, v15
	v_cvt_pk_bf16_f32 v12, v12, v13
	v_cvt_pk_bf16_f32 v13, v16, v17
	v_add_u32_e32 v8, 0x20000, v7
	global_store_dwordx4 v8, v[10:13], s[8:9] offset:1024
	s_waitcnt vmcnt(27)
	v_max3_f32 v5, v108, v109, v110
	v_sub_f32_e32 v9, v108, v5
	v_sub_f32_e32 v40, v109, v5
	v_and_b32_e32 v27, 0xffff0000, v97
	v_lshlrev_b32_e32 v28, 16, v97
	v_sub_f32_e32 v5, v110, v5
	v_lshlrev_b32_e32 v24, 16, v100
	v_and_b32_e32 v11, 0xffff0000, v100
	v_lshlrev_b32_e32 v38, 16, v104
	v_and_b32_e32 v39, 0xffff0000, v104
	v_lshlrev_b32_e32 v26, 16, v101
	v_and_b32_e32 v29, 0xffff0000, v101
	v_lshlrev_b32_e32 v14, 16, v105
	v_and_b32_e32 v15, 0xffff0000, v105
	v_lshlrev_b32_e32 v18, 16, v106
	v_and_b32_e32 v19, 0xffff0000, v106
	v_mul_f32_e32 v9, 0x3fb8aa3b, v9
	v_mul_f32_e32 v20, 0x3fb8aa3b, v40
	v_and_b32_e32 v35, 0xffff0000, v99
	v_lshlrev_b32_e32 v36, 16, v99
	v_lshlrev_b32_e32 v30, 16, v102
	v_and_b32_e32 v13, 0xffff0000, v102
	v_lshlrev_b32_e32 v34, 16, v103
	v_and_b32_e32 v37, 0xffff0000, v103
	v_lshlrev_b32_e32 v16, 16, v107
	v_and_b32_e32 v17, 0xffff0000, v107
	v_mul_f32_e32 v5, 0x3fb8aa3b, v5
	v_exp_f32_e32 v21, v9
	v_exp_f32_e32 v20, v20
	v_exp_f32_e32 v5, v5
	v_and_b32_e32 v25, 0xffff0000, v96
	v_lshlrev_b32_e32 v10, 16, v96
	v_add_f32_e32 v9, v21, v20
	v_add_f32_e32 v9, v5, v9
	v_and_b32_e32 v31, 0xffff0000, v98
	v_rcp_f32_e32 v40, v9
	s_nop 0
	v_lshlrev_b32_e32 v12, 16, v98
	v_pk_mul_f32 v[20:21], v[20:21], v[40:41] op_sel_hi:[1,0]
	v_mul_f32_e32 v42, v5, v40
	v_pk_mul_f32 v[10:11], v[20:21], v[10:11] op_sel:[1,0] op_sel_hi:[0,1]
	v_pk_mul_f32 v[28:29], v[20:21], v[28:29] op_sel:[1,0] op_sel_hi:[0,1]
	v_pk_mul_f32 v[12:13], v[20:21], v[12:13] op_sel:[1,0] op_sel_hi:[0,1]
	v_pk_mul_f32 v[36:37], v[20:21], v[36:37] op_sel:[1,0] op_sel_hi:[0,1]
	v_pk_fma_f32 v[10:11], v[20:21], v[24:25], v[10:11]
	v_pk_fma_f32 v[24:25], v[20:21], v[26:27], v[28:29]
	v_pk_fma_f32 v[12:13], v[20:21], v[30:31], v[12:13]
	v_pk_fma_f32 v[20:21], v[20:21], v[34:35], v[36:37]
	v_pk_fma_f32 v[10:11], v[42:43], v[38:39], v[10:11] op_sel_hi:[0,1,1]
	v_pk_fma_f32 v[14:15], v[42:43], v[14:15], v[24:25] op_sel_hi:[0,1,1]
	v_pk_fma_f32 v[12:13], v[42:43], v[18:19], v[12:13] op_sel_hi:[0,1,1]
	v_pk_fma_f32 v[16:17], v[42:43], v[16:17], v[20:21] op_sel_hi:[0,1,1]
	v_cvt_pk_bf16_f32 v10, v10, v11
	v_cvt_pk_bf16_f32 v11, v14, v15
	v_cvt_pk_bf16_f32 v12, v12, v13
	v_cvt_pk_bf16_f32 v13, v16, v17
	v_add_u32_e32 v8, 0x30000, v7
	global_store_dwordx4 v8, v[10:13], s[8:9] offset:1024
	s_waitcnt vmcnt(22)
	v_max3_f32 v5, v140, v141, v142
	v_sub_f32_e32 v9, v140, v5
	v_sub_f32_e32 v40, v141, v5
	v_and_b32_e32 v27, 0xffff0000, v129
	v_lshlrev_b32_e32 v28, 16, v129
	v_sub_f32_e32 v5, v142, v5
	v_lshlrev_b32_e32 v24, 16, v132
	v_and_b32_e32 v11, 0xffff0000, v132
	v_lshlrev_b32_e32 v38, 16, v136
	v_and_b32_e32 v39, 0xffff0000, v136
	v_lshlrev_b32_e32 v26, 16, v133
	v_and_b32_e32 v29, 0xffff0000, v133
	v_lshlrev_b32_e32 v14, 16, v137
	v_and_b32_e32 v15, 0xffff0000, v137
	v_lshlrev_b32_e32 v18, 16, v138
	v_and_b32_e32 v19, 0xffff0000, v138
	v_mul_f32_e32 v9, 0x3fb8aa3b, v9
	v_mul_f32_e32 v20, 0x3fb8aa3b, v40
	v_and_b32_e32 v35, 0xffff0000, v131
	v_lshlrev_b32_e32 v36, 16, v131
	v_lshlrev_b32_e32 v30, 16, v134
	v_and_b32_e32 v13, 0xffff0000, v134
	v_lshlrev_b32_e32 v34, 16, v135
	v_and_b32_e32 v37, 0xffff0000, v135
	v_lshlrev_b32_e32 v16, 16, v139
	v_and_b32_e32 v17, 0xffff0000, v139
	v_mul_f32_e32 v5, 0x3fb8aa3b, v5
	v_exp_f32_e32 v21, v9
	v_exp_f32_e32 v20, v20
	v_exp_f32_e32 v5, v5
	v_and_b32_e32 v25, 0xffff0000, v128
	v_lshlrev_b32_e32 v10, 16, v128
	v_add_f32_e32 v9, v21, v20
	v_add_f32_e32 v9, v5, v9
	v_and_b32_e32 v31, 0xffff0000, v130
	v_rcp_f32_e32 v40, v9
	s_nop 0
	v_lshlrev_b32_e32 v12, 16, v130
	v_pk_mul_f32 v[20:21], v[20:21], v[40:41] op_sel_hi:[1,0]
	v_mul_f32_e32 v42, v5, v40
	v_pk_mul_f32 v[10:11], v[20:21], v[10:11] op_sel:[1,0] op_sel_hi:[0,1]
	v_pk_mul_f32 v[28:29], v[20:21], v[28:29] op_sel:[1,0] op_sel_hi:[0,1]
	v_pk_mul_f32 v[12:13], v[20:21], v[12:13] op_sel:[1,0] op_sel_hi:[0,1]
	v_pk_mul_f32 v[36:37], v[20:21], v[36:37] op_sel:[1,0] op_sel_hi:[0,1]
	v_pk_fma_f32 v[10:11], v[20:21], v[24:25], v[10:11]
	v_pk_fma_f32 v[24:25], v[20:21], v[26:27], v[28:29]
	v_pk_fma_f32 v[12:13], v[20:21], v[30:31], v[12:13]
	v_pk_fma_f32 v[20:21], v[20:21], v[34:35], v[36:37]
	v_pk_fma_f32 v[10:11], v[42:43], v[38:39], v[10:11] op_sel_hi:[0,1,1]
	v_pk_fma_f32 v[14:15], v[42:43], v[14:15], v[24:25] op_sel_hi:[0,1,1]
	v_pk_fma_f32 v[12:13], v[42:43], v[18:19], v[12:13] op_sel_hi:[0,1,1]
	v_pk_fma_f32 v[16:17], v[42:43], v[16:17], v[20:21] op_sel_hi:[0,1,1]
	v_cvt_pk_bf16_f32 v10, v10, v11
	v_cvt_pk_bf16_f32 v11, v14, v15
	v_cvt_pk_bf16_f32 v12, v12, v13
	v_cvt_pk_bf16_f32 v13, v16, v17
	v_add_u32_e32 v8, 0x40000, v7
	global_store_dwordx4 v8, v[10:13], s[8:9] offset:1024
	s_waitcnt vmcnt(17)
	v_max3_f32 v5, v164, v165, v166
	v_sub_f32_e32 v9, v164, v5
	v_sub_f32_e32 v40, v165, v5
	v_and_b32_e32 v27, 0xffff0000, v153
	v_lshlrev_b32_e32 v28, 16, v153
	v_sub_f32_e32 v5, v166, v5
	v_lshlrev_b32_e32 v24, 16, v156
	v_and_b32_e32 v11, 0xffff0000, v156
	v_lshlrev_b32_e32 v38, 16, v160
	v_and_b32_e32 v39, 0xffff0000, v160
	v_lshlrev_b32_e32 v26, 16, v157
	v_and_b32_e32 v29, 0xffff0000, v157
	v_lshlrev_b32_e32 v14, 16, v161
	v_and_b32_e32 v15, 0xffff0000, v161
	v_lshlrev_b32_e32 v18, 16, v162
	v_and_b32_e32 v19, 0xffff0000, v162
	v_mul_f32_e32 v9, 0x3fb8aa3b, v9
	v_mul_f32_e32 v20, 0x3fb8aa3b, v40
	v_and_b32_e32 v35, 0xffff0000, v155
	v_lshlrev_b32_e32 v36, 16, v155
	v_lshlrev_b32_e32 v30, 16, v158
	v_and_b32_e32 v13, 0xffff0000, v158
	v_lshlrev_b32_e32 v34, 16, v159
	v_and_b32_e32 v37, 0xffff0000, v159
	v_lshlrev_b32_e32 v16, 16, v163
	v_and_b32_e32 v17, 0xffff0000, v163
	v_mul_f32_e32 v5, 0x3fb8aa3b, v5
	v_exp_f32_e32 v21, v9
	v_exp_f32_e32 v20, v20
	v_exp_f32_e32 v5, v5
	v_and_b32_e32 v25, 0xffff0000, v152
	v_lshlrev_b32_e32 v10, 16, v152
	v_add_f32_e32 v9, v21, v20
	v_add_f32_e32 v9, v5, v9
	v_and_b32_e32 v31, 0xffff0000, v154
	v_rcp_f32_e32 v40, v9
	s_nop 0
	v_lshlrev_b32_e32 v12, 16, v154
	v_pk_mul_f32 v[20:21], v[20:21], v[40:41] op_sel_hi:[1,0]
	v_mul_f32_e32 v42, v5, v40
	v_pk_mul_f32 v[10:11], v[20:21], v[10:11] op_sel:[1,0] op_sel_hi:[0,1]
	v_pk_mul_f32 v[28:29], v[20:21], v[28:29] op_sel:[1,0] op_sel_hi:[0,1]
	v_pk_mul_f32 v[12:13], v[20:21], v[12:13] op_sel:[1,0] op_sel_hi:[0,1]
	v_pk_mul_f32 v[36:37], v[20:21], v[36:37] op_sel:[1,0] op_sel_hi:[0,1]
	v_pk_fma_f32 v[10:11], v[20:21], v[24:25], v[10:11]
	v_pk_fma_f32 v[24:25], v[20:21], v[26:27], v[28:29]
	v_pk_fma_f32 v[12:13], v[20:21], v[30:31], v[12:13]
	v_pk_fma_f32 v[20:21], v[20:21], v[34:35], v[36:37]
	v_pk_fma_f32 v[10:11], v[42:43], v[38:39], v[10:11] op_sel_hi:[0,1,1]
	v_pk_fma_f32 v[14:15], v[42:43], v[14:15], v[24:25] op_sel_hi:[0,1,1]
	v_pk_fma_f32 v[12:13], v[42:43], v[18:19], v[12:13] op_sel_hi:[0,1,1]
	v_pk_fma_f32 v[16:17], v[42:43], v[16:17], v[20:21] op_sel_hi:[0,1,1]
	v_cvt_pk_bf16_f32 v10, v10, v11
	v_cvt_pk_bf16_f32 v11, v14, v15
	v_cvt_pk_bf16_f32 v12, v12, v13
	v_cvt_pk_bf16_f32 v13, v16, v17
	v_add_u32_e32 v8, 0x50000, v7
	global_store_dwordx4 v8, v[10:13], s[8:9] offset:1024
	s_waitcnt vmcnt(12)
	v_max3_f32 v5, v218, v219, v220
	v_sub_f32_e32 v9, v218, v5
	v_sub_f32_e32 v40, v219, v5
	v_and_b32_e32 v27, 0xffff0000, v207
	v_lshlrev_b32_e32 v28, 16, v207
	v_sub_f32_e32 v5, v220, v5
	v_lshlrev_b32_e32 v24, 16, v210
	v_and_b32_e32 v11, 0xffff0000, v210
	v_lshlrev_b32_e32 v38, 16, v214
	v_and_b32_e32 v39, 0xffff0000, v214
	v_lshlrev_b32_e32 v26, 16, v211
	v_and_b32_e32 v29, 0xffff0000, v211
	v_lshlrev_b32_e32 v14, 16, v215
	v_and_b32_e32 v15, 0xffff0000, v215
	v_lshlrev_b32_e32 v18, 16, v216
	v_and_b32_e32 v19, 0xffff0000, v216
	v_mul_f32_e32 v9, 0x3fb8aa3b, v9
	v_mul_f32_e32 v20, 0x3fb8aa3b, v40
	v_and_b32_e32 v35, 0xffff0000, v209
	v_lshlrev_b32_e32 v36, 16, v209
	v_lshlrev_b32_e32 v30, 16, v212
	v_and_b32_e32 v13, 0xffff0000, v212
	v_lshlrev_b32_e32 v34, 16, v213
	v_and_b32_e32 v37, 0xffff0000, v213
	v_lshlrev_b32_e32 v16, 16, v217
	v_and_b32_e32 v17, 0xffff0000, v217
	v_mul_f32_e32 v5, 0x3fb8aa3b, v5
	v_exp_f32_e32 v21, v9
	v_exp_f32_e32 v20, v20
	v_exp_f32_e32 v5, v5
	v_and_b32_e32 v25, 0xffff0000, v206
	v_lshlrev_b32_e32 v10, 16, v206
	v_add_f32_e32 v9, v21, v20
	v_add_f32_e32 v9, v5, v9
	v_and_b32_e32 v31, 0xffff0000, v208
	v_rcp_f32_e32 v40, v9
	s_nop 0
	v_lshlrev_b32_e32 v12, 16, v208
	v_pk_mul_f32 v[20:21], v[20:21], v[40:41] op_sel_hi:[1,0]
	v_mul_f32_e32 v42, v5, v40
	v_pk_mul_f32 v[10:11], v[20:21], v[10:11] op_sel:[1,0] op_sel_hi:[0,1]
	v_pk_mul_f32 v[28:29], v[20:21], v[28:29] op_sel:[1,0] op_sel_hi:[0,1]
	v_pk_mul_f32 v[12:13], v[20:21], v[12:13] op_sel:[1,0] op_sel_hi:[0,1]
	v_pk_mul_f32 v[36:37], v[20:21], v[36:37] op_sel:[1,0] op_sel_hi:[0,1]
	v_pk_fma_f32 v[10:11], v[20:21], v[24:25], v[10:11]
	v_pk_fma_f32 v[24:25], v[20:21], v[26:27], v[28:29]
	v_pk_fma_f32 v[12:13], v[20:21], v[30:31], v[12:13]
	v_pk_fma_f32 v[20:21], v[20:21], v[34:35], v[36:37]
	v_pk_fma_f32 v[10:11], v[42:43], v[38:39], v[10:11] op_sel_hi:[0,1,1]
	v_pk_fma_f32 v[14:15], v[42:43], v[14:15], v[24:25] op_sel_hi:[0,1,1]
	v_pk_fma_f32 v[12:13], v[42:43], v[18:19], v[12:13] op_sel_hi:[0,1,1]
	v_pk_fma_f32 v[16:17], v[42:43], v[16:17], v[20:21] op_sel_hi:[0,1,1]
	v_cvt_pk_bf16_f32 v10, v10, v11
	v_cvt_pk_bf16_f32 v11, v14, v15
	v_cvt_pk_bf16_f32 v12, v12, v13
	v_cvt_pk_bf16_f32 v13, v16, v17
	v_add_u32_e32 v8, 0x60000, v7
	global_store_dwordx4 v8, v[10:13], s[8:9] offset:1024
	s_waitcnt vmcnt(7)
	v_max3_f32 v5, v244, v245, v246
	v_sub_f32_e32 v9, v244, v5
	v_sub_f32_e32 v40, v245, v5
	v_and_b32_e32 v27, 0xffff0000, v233
	v_lshlrev_b32_e32 v28, 16, v233
	v_sub_f32_e32 v5, v246, v5
	v_lshlrev_b32_e32 v24, 16, v236
	v_and_b32_e32 v11, 0xffff0000, v236
	v_lshlrev_b32_e32 v38, 16, v240
	v_and_b32_e32 v39, 0xffff0000, v240
	v_lshlrev_b32_e32 v26, 16, v237
	v_and_b32_e32 v29, 0xffff0000, v237
	v_lshlrev_b32_e32 v14, 16, v241
	v_and_b32_e32 v15, 0xffff0000, v241
	v_lshlrev_b32_e32 v18, 16, v242
	v_and_b32_e32 v19, 0xffff0000, v242
	v_mul_f32_e32 v9, 0x3fb8aa3b, v9
	v_mul_f32_e32 v20, 0x3fb8aa3b, v40
	v_and_b32_e32 v35, 0xffff0000, v235
	v_lshlrev_b32_e32 v36, 16, v235
	v_lshlrev_b32_e32 v30, 16, v238
	v_and_b32_e32 v13, 0xffff0000, v238
	v_lshlrev_b32_e32 v34, 16, v239
	v_and_b32_e32 v37, 0xffff0000, v239
	v_lshlrev_b32_e32 v16, 16, v243
	v_and_b32_e32 v17, 0xffff0000, v243
	v_mul_f32_e32 v5, 0x3fb8aa3b, v5
	v_exp_f32_e32 v21, v9
	v_exp_f32_e32 v20, v20
	v_exp_f32_e32 v5, v5
	v_and_b32_e32 v25, 0xffff0000, v232
	v_lshlrev_b32_e32 v10, 16, v232
	v_add_f32_e32 v9, v21, v20
	v_add_f32_e32 v9, v5, v9
	v_and_b32_e32 v31, 0xffff0000, v234
	v_rcp_f32_e32 v40, v9
	s_nop 0
	v_lshlrev_b32_e32 v12, 16, v234
	v_pk_mul_f32 v[20:21], v[20:21], v[40:41] op_sel_hi:[1,0]
	v_mul_f32_e32 v42, v5, v40
	v_pk_mul_f32 v[10:11], v[20:21], v[10:11] op_sel:[1,0] op_sel_hi:[0,1]
	v_pk_mul_f32 v[28:29], v[20:21], v[28:29] op_sel:[1,0] op_sel_hi:[0,1]
	v_pk_mul_f32 v[12:13], v[20:21], v[12:13] op_sel:[1,0] op_sel_hi:[0,1]
	v_pk_mul_f32 v[36:37], v[20:21], v[36:37] op_sel:[1,0] op_sel_hi:[0,1]
	v_pk_fma_f32 v[10:11], v[20:21], v[24:25], v[10:11]
	v_pk_fma_f32 v[24:25], v[20:21], v[26:27], v[28:29]
	v_pk_fma_f32 v[12:13], v[20:21], v[30:31], v[12:13]
	v_pk_fma_f32 v[20:21], v[20:21], v[34:35], v[36:37]
	v_pk_fma_f32 v[10:11], v[42:43], v[38:39], v[10:11] op_sel_hi:[0,1,1]
	v_pk_fma_f32 v[14:15], v[42:43], v[14:15], v[24:25] op_sel_hi:[0,1,1]
	v_pk_fma_f32 v[12:13], v[42:43], v[18:19], v[12:13] op_sel_hi:[0,1,1]
	v_pk_fma_f32 v[16:17], v[42:43], v[16:17], v[20:21] op_sel_hi:[0,1,1]
	v_cvt_pk_bf16_f32 v10, v10, v11
	v_cvt_pk_bf16_f32 v11, v14, v15
	v_cvt_pk_bf16_f32 v12, v12, v13
	v_cvt_pk_bf16_f32 v13, v16, v17
	v_add_u32_e32 v8, 0x70000, v7
	global_store_dwordx4 v8, v[10:13], s[8:9] offset:1024
	s_cmp_eq_u32 s99, 1
	s_cbranch_scc0 .Lcomb_end
	s_mov_b32 s99, 2
	s_branch .Lretb_start
.Lcomb_end:
	s_waitcnt vmcnt(0)
	s_barrier
	s_mov_b64 s[0:1], exec
	v_readlane_b32 s2, v254, 29
	v_readlane_b32 s3, v254, 30
	s_and_b64 s[2:3], s[0:1], s[2:3]
	s_mov_b64 exec, s[2:3]
	s_cbranch_execz .LBB0_605
	s_andn2_b64 vcc, exec, s[42:43]
	s_cbranch_vccnz .LBB0_594
	buffer_wbl2 sc1
	s_waitcnt vmcnt(0)
	s_waitcnt vmcnt(0)
